# in-projection GEMM: last partial round (80 tiles) computed as 160 half tiles, two workgroups per tile
# speedup vs baseline: 1.0041x; 1.0030x over previous
.LBB0_295:
	s_add_u32 s36, s36, 0x21e24000
	s_addc_u32 s37, s37, 0
	s_lshl_b32 s13, s38, 5
	s_and_b32 s13, s13, 0x60
	s_lshl_b32 s12, s11, 13
	s_lshl_b32 s40, s13, 7
	s_add_u32 s38, s20, 0x8000
	v_mov_b32_e32 v137, v99
	s_addc_u32 s39, s21, 0
	v_mov_b32_e32 v133, v99
	s_add_i32 m0, s59, 0x18000
	v_lshl_add_u64 v[14:15], s[38:39], 0, v[136:137]
	s_waitcnt vmcnt(2)
	s_barrier
	global_load_lds_dwordx4 v[14:15], off
	v_lshl_add_u64 v[14:15], s[38:39], 0, v[132:133]
	s_add_i32 m0, s59, 0x1a000
	s_add_i32 s63, s59, 0x8000
	s_add_i32 s64, s59, 0xa000
	global_load_lds_dwordx4 v[14:15], off
	v_lshl_add_u64 v[2:3], v[2:3], 0, s[24:25]
	s_mov_b32 m0, s63
	s_add_u32 s38, s20, 0xc000
	global_load_lds_dwordx4 v[2:3], off
	v_lshl_add_u64 v[2:3], v[4:5], 0, s[24:25]
	s_mov_b32 m0, s64
	s_addc_u32 s39, s21, 0
	global_load_lds_dwordx4 v[2:3], off
	s_add_i32 m0, s59, 0x1c000
	v_lshl_add_u64 v[2:3], s[38:39], 0, v[136:137]
	global_load_lds_dwordx4 v[2:3], off
	v_lshl_add_u64 v[2:3], s[38:39], 0, v[132:133]
	s_add_i32 m0, s59, 0x1e000
	s_cmpk_lt_u32 s10, 0x100
	global_load_lds_dwordx4 v[2:3], off
	v_lshrrev_b32_e32 v3, 1, v6
	v_and_b32_e32 v3, 24, v3
	v_and_b32_e32 v2, 15, v6
	v_lshlrev_b32_e32 v4, 1, v3
	v_lshl_or_b32 v146, s11, 6, v2
	v_lshl_or_b32 v2, v2, 6, v4
	v_lshlrev_b32_e32 v4, 2, v6
	v_and_b32_e32 v4, 32, v4
	v_bitop3_b32 v5, v2, s12, v4 bitop3:0xde
	v_bitop3_b32 v147, v2, s40, v4 bitop3:0xde
	v_lshlrev_b32_e32 v2, 15, v11
	v_and_b32_e32 v2, 0xffff0000, v2
	v_or_b32_e32 v148, s13, v3
	v_lshl_add_u32 v2, v10, 12, v2
	v_and_b32_e32 v3, 1, v11
	v_lshl_or_b32 v2, v3, 6, v2
	v_lshl_add_u32 v138, v12, 1, v2
	v_lshlrev_b32_e32 v2, 15, v7
	v_and_b32_e32 v2, 0xffff0000, v2
	s_waitcnt vmcnt(6)
	v_lshl_add_u32 v2, v8, 12, v2
	v_and_b32_e32 v3, 1, v7
	v_lshl_or_b32 v2, v3, 6, v2
	v_readlane_b32 s10, v254, 26
	s_cselect_b64 s[38:39], -1, 0
	s_ashr_i32 s65, s6, 31
	v_mov_b32_e32 v139, v99
	v_lshl_add_u32 v140, v9, 1, v2
	v_mov_b32_e32 v141, v99
	s_mov_b32 s66, 0
	v_add_u32_e32 v149, 0, v5
	v_readlane_b32 s67, v254, 25
	s_mov_b32 s68, s10
	s_barrier
	v_readlane_b32 s11, v254, 27
	s_mov_b32 s100, 0
	s_branch .LBB0_298

.LBB0_297:
	s_mov_b32 s100, s101
	s_andn2_b64 vcc, exec, s[20:21]
	s_mov_b32 s67, s42
	s_mov_b32 s68, s44
	s_mov_b64 s[20:21], s[48:49]
	s_mov_b64 s[54:55], s[46:47]
	s_cbranch_vccz .LBB0_307
.LBB0_298:
	s_add_i32 s66, s66, 1
	s_mul_i32 s10, s66, s65
	s_mul_hi_u32 s11, s66, s6
	s_add_i32 s11, s11, s10
	s_mul_i32 s10, s66, s6
	s_add_u32 s46, s10, s2
	s_addc_u32 s47, s11, s3
	s_mov_b32 s101, 0
	s_cmp_lg_u32 s6, 0x100
	s_cbranch_scc1 .Lgi_sched_done
	s_cmp_lg_u32 s66, 5
	s_cbranch_scc1 .Lgi_sched_done
	s_movk_i32 s46, 0x7d0
	s_mov_b32 s47, 0
	s_cmpk_gt_u32 s2, 0x9f
	s_cbranch_scc1 .Lgi_sched_done
	s_lshr_b32 s46, s2, 1
	s_add_i32 s46, s46, 0x500
	s_and_b32 s101, s2, 1
	s_add_i32 s101, s101, 1
.Lgi_sched_done:
	v_mov_b64_e32 v[2:3], 0x54f
	v_cmp_gt_i64_e32 vcc, s[46:47], v[2:3]
	v_cmp_lt_i64_e64 s[40:41], s[46:47], v[250:251]
	s_cbranch_vccnz .LBB0_300
	s_ashr_i32 s10, s46, 31
	s_lshr_b32 s10, s10, 29
	s_add_i32 s10, s46, s10
	s_ashr_i32 s11, s10, 3
	s_and_b32 s10, s10, -8
	s_sub_i32 s10, s46, s10
	s_cmp_lt_i32 s10, 0
	s_movk_i32 s12, 0xab
	s_cselect_b32 s12, s12, 0xaa
	s_mul_i32 s10, s12, s10
	s_add_i32 s10, s10, s11
	s_mul_hi_i32 s11, s10, 0x66666667
	s_lshr_b32 s12, s11, 31
	s_ashr_i32 s11, s11, 5
	s_add_i32 s11, s11, s12
	s_lshl_b32 s12, s11, 2
	s_sub_i32 s13, 0x44, s12
	s_min_i32 s13, s13, 4
	s_abs_i32 s42, s13
	v_cvt_f32_u32_e32 v2, s42
	s_sub_i32 s44, 0, s42
	s_mulk_i32 s11, 0x50
	s_sub_i32 s10, s10, s11
	v_rcp_iflag_f32_e32 v2, v2
	s_abs_i32 s11, s10
	s_xor_b32 s43, s10, s13
	s_ashr_i32 s43, s43, 31
	v_mul_f32_e32 v2, 0x4f7ffffe, v2
	v_cvt_u32_f32_e32 v2, v2
	s_nop 0
	v_readfirstlane_b32 s45, v2
	s_mul_i32 s44, s44, s45
	s_mul_hi_u32 s44, s45, s44
	s_add_i32 s45, s45, s44
	s_mul_hi_u32 s44, s11, s45
	s_mul_i32 s45, s44, s42
	s_sub_i32 s11, s11, s45
	s_add_i32 s46, s44, 1
	s_sub_i32 s45, s11, s42
	s_cmp_ge_u32 s11, s42
	s_cselect_b32 s44, s46, s44
	s_cselect_b32 s11, s45, s11
	s_add_i32 s45, s44, 1
	s_cmp_ge_u32 s11, s42
	s_cselect_b32 s11, s45, s44
	s_xor_b32 s11, s11, s43
	s_sub_i32 s42, s11, s43
	s_mul_i32 s11, s42, s13
	s_sub_i32 s10, s10, s11
	s_add_i32 s44, s10, s12
.LBB0_300:
	s_ashr_i32 s45, s44, 31
	s_lshl_b64 s[10:11], s[44:45], 20
	s_add_u32 s46, s7, s10
	s_addc_u32 s47, s8, s11
	s_and_b64 s[10:11], s[40:41], exec
	s_cselect_b32 s45, s47, s55
	s_cselect_b32 s69, s46, s54
	s_ashr_i32 s43, s42, 31
	s_lshl_b64 s[10:11], s[42:43], 20
	s_add_u32 s48, s9, s10
	s_addc_u32 s49, s52, s11
	s_and_b64 s[10:11], s[40:41], exec
	s_cselect_b32 s43, s49, s21
	s_cselect_b32 s70, s48, s20
	s_add_u32 s71, s20, 0x10000
	s_addc_u32 s72, s21, 0
	s_add_u32 s54, s54, 0x80080
	v_mov_b32_e32 v2, 0
	s_addc_u32 s55, s55, 0
	s_mov_b32 s73, -2
	v_mov_b32_e32 v3, v2
	v_mov_b32_e32 v4, v2
	v_mov_b32_e32 v5, v2
	v_mov_b32_e32 v6, v2
	v_mov_b32_e32 v7, v2
	v_mov_b32_e32 v8, v2
	v_mov_b32_e32 v9, v2
	v_mov_b32_e32 v10, v2
	v_mov_b32_e32 v11, v2
	v_mov_b32_e32 v12, v2
	v_mov_b32_e32 v13, v2
	v_mov_b32_e32 v18, v2
	v_mov_b32_e32 v19, v2
	v_mov_b32_e32 v20, v2
	v_mov_b32_e32 v21, v2
	v_mov_b32_e32 v26, v2
	v_mov_b32_e32 v27, v2
	v_mov_b32_e32 v28, v2
	v_mov_b32_e32 v29, v2
	v_mov_b32_e32 v34, v2
	v_mov_b32_e32 v35, v2
	v_mov_b32_e32 v36, v2
	v_mov_b32_e32 v37, v2
	v_mov_b32_e32 v42, v2
	v_mov_b32_e32 v43, v2
	v_mov_b32_e32 v44, v2
	v_mov_b32_e32 v45, v2
	v_mov_b32_e32 v50, v2
	v_mov_b32_e32 v51, v2
	v_mov_b32_e32 v52, v2
	v_mov_b32_e32 v53, v2
	v_mov_b32_e32 v14, v2
	v_mov_b32_e32 v15, v2
	v_mov_b32_e32 v16, v2
	v_mov_b32_e32 v17, v2
	v_mov_b32_e32 v22, v2
	v_mov_b32_e32 v23, v2
	v_mov_b32_e32 v24, v2
	v_mov_b32_e32 v25, v2
	v_mov_b32_e32 v30, v2
	v_mov_b32_e32 v31, v2
	v_mov_b32_e32 v32, v2
	v_mov_b32_e32 v33, v2
	v_mov_b32_e32 v38, v2
	v_mov_b32_e32 v39, v2
	v_mov_b32_e32 v40, v2
	v_mov_b32_e32 v41, v2
	v_mov_b32_e32 v46, v2
	v_mov_b32_e32 v47, v2
	v_mov_b32_e32 v48, v2
	v_mov_b32_e32 v49, v2
	v_mov_b32_e32 v54, v2
	v_mov_b32_e32 v55, v2
	v_mov_b32_e32 v56, v2
	v_mov_b32_e32 v57, v2
	v_mov_b32_e32 v58, v2
	v_mov_b32_e32 v59, v2
	v_mov_b32_e32 v60, v2
	v_mov_b32_e32 v61, v2
	v_mov_b32_e32 v62, v2
	v_mov_b32_e32 v63, v2
	v_mov_b32_e32 v64, v2
	v_mov_b32_e32 v65, v2
	v_mov_b32_e32 v66, v2
	v_mov_b32_e32 v67, v2
	v_mov_b32_e32 v68, v2
	v_mov_b32_e32 v69, v2
	v_mov_b32_e32 v70, v2
	v_mov_b32_e32 v71, v2
	v_mov_b32_e32 v72, v2
	v_mov_b32_e32 v73, v2
	v_mov_b32_e32 v74, v2
	v_mov_b32_e32 v75, v2
	v_mov_b32_e32 v76, v2
	v_mov_b32_e32 v77, v2
	v_mov_b32_e32 v82, v2
	v_mov_b32_e32 v83, v2
	v_mov_b32_e32 v84, v2
	v_mov_b32_e32 v85, v2
	v_mov_b32_e32 v90, v2
	v_mov_b32_e32 v91, v2
	v_mov_b32_e32 v92, v2
	v_mov_b32_e32 v93, v2
	v_mov_b32_e32 v100, v2
	v_mov_b32_e32 v101, v2
	v_mov_b32_e32 v102, v2
	v_mov_b32_e32 v103, v2
	v_mov_b32_e32 v108, v2
	v_mov_b32_e32 v109, v2
	v_mov_b32_e32 v110, v2
	v_mov_b32_e32 v111, v2
	v_mov_b32_e32 v116, v2
	v_mov_b32_e32 v117, v2
	v_mov_b32_e32 v118, v2
	v_mov_b32_e32 v119, v2
	v_mov_b32_e32 v78, v2
	v_mov_b32_e32 v79, v2
	v_mov_b32_e32 v80, v2
	v_mov_b32_e32 v81, v2
	v_mov_b32_e32 v86, v2
	v_mov_b32_e32 v87, v2
	v_mov_b32_e32 v88, v2
	v_mov_b32_e32 v89, v2
	v_mov_b32_e32 v94, v2
	v_mov_b32_e32 v95, v2
	v_mov_b32_e32 v96, v2
	v_mov_b32_e32 v97, v2
	v_mov_b32_e32 v104, v2
	v_mov_b32_e32 v105, v2
	v_mov_b32_e32 v106, v2
	v_mov_b32_e32 v107, v2
	v_mov_b32_e32 v112, v2
	v_mov_b32_e32 v113, v2
	v_mov_b32_e32 v114, v2
	v_mov_b32_e32 v115, v2
	v_mov_b32_e32 v120, v2
	v_mov_b32_e32 v121, v2
	v_mov_b32_e32 v122, v2
	v_mov_b32_e32 v123, v2
	v_mov_b32_e32 v124, v2
	v_mov_b32_e32 v125, v2
	v_mov_b32_e32 v126, v2
	v_mov_b32_e32 v127, v2
	v_mov_b32_e32 v128, v2
	v_mov_b32_e32 v129, v2
	v_mov_b32_e32 v130, v2
	v_mov_b32_e32 v131, v2
	s_cmp_eq_u32 s100, 1
	s_cbranch_scc1 .Lgi_h0_loop
	s_cmp_eq_u32 s100, 2
	s_cbranch_scc1 .Lgi_h1_loop

.Lgi_after_loop:
	s_and_b64 vcc, exec, s[38:39]
	s_cbranch_vccz .LBB0_304
	s_barrier
.LBB0_304:
	v_lshl_or_b32 v144, s67, 8, v148
	v_lshl_add_u32 v152, s68, 8, v146
	v_ashrrev_i32_e32 v145, 31, v144
	v_mov_b64_e32 v[142:143], s[36:37]
	v_mad_i64_i32 v[150:151], s[10:11], v152, s29, v[142:143]
	v_lshlrev_b64 v[144:145], 1, v[144:145]
	v_lshl_add_u64 v[150:151], v[150:151], 0, v[144:145]
	v_cvt_pk_bf16_f32 v128, v128, v129
	v_cvt_pk_bf16_f32 v129, v130, v131
	v_cvt_pk_bf16_f32 v130, v124, v125
	v_cvt_pk_bf16_f32 v131, v126, v127
	s_cmp_eq_u32 s100, 2
	s_cbranch_scc1 .Lgi_st0
	global_store_dwordx4 v[150:151], v[128:131], off
.Lgi_st0:
	v_cvt_pk_bf16_f32 v116, v116, v117
	v_cvt_pk_bf16_f32 v117, v118, v119
	v_cvt_pk_bf16_f32 v118, v108, v109
	v_or_b32_e32 v108, 16, v152
	v_mad_i64_i32 v[108:109], s[10:11], v108, s29, v[142:143]
	v_cvt_pk_bf16_f32 v119, v110, v111
	s_cmp_eq_u32 s100, 1
	s_cbranch_scc1 .Lgi_st1
	global_store_dwordx4 v[150:151], v[116:119], off offset:256
.Lgi_st1:
	s_andn2_b64 vcc, exec, s[40:41]
	s_mov_b64 s[20:21], -1
	v_lshl_add_u64 v[116:117], v[108:109], 0, v[144:145]
	v_cvt_pk_bf16_f32 v108, v120, v121
	v_cvt_pk_bf16_f32 v109, v122, v123
	v_cvt_pk_bf16_f32 v110, v112, v113
	v_cvt_pk_bf16_f32 v111, v114, v115
	s_cmp_eq_u32 s100, 2
	s_cbranch_scc1 .Lgi_st2
	global_store_dwordx4 v[116:117], v[108:111], off
.Lgi_st2:
	v_cvt_pk_bf16_f32 v100, v100, v101
	v_cvt_pk_bf16_f32 v101, v102, v103
	v_cvt_pk_bf16_f32 v102, v90, v91
	v_or_b32_e32 v90, 32, v152
	v_mad_i64_i32 v[90:91], s[10:11], v90, s29, v[142:143]
	v_cvt_pk_bf16_f32 v103, v92, v93
	s_cmp_eq_u32 s100, 1
	s_cbranch_scc1 .Lgi_st3
	global_store_dwordx4 v[116:117], v[100:103], off offset:256
.Lgi_st3:
	s_nop 1
	v_lshl_add_u64 v[100:101], v[90:91], 0, v[144:145]
	v_cvt_pk_bf16_f32 v90, v104, v105
	v_cvt_pk_bf16_f32 v91, v106, v107
	v_cvt_pk_bf16_f32 v92, v94, v95
	v_cvt_pk_bf16_f32 v93, v96, v97
	s_cmp_eq_u32 s100, 2
	s_cbranch_scc1 .Lgi_st4
	global_store_dwordx4 v[100:101], v[90:93], off
.Lgi_st4:
	v_cvt_pk_bf16_f32 v82, v82, v83
	v_cvt_pk_bf16_f32 v83, v84, v85
	v_cvt_pk_bf16_f32 v84, v74, v75
	v_or_b32_e32 v74, 48, v152
	v_mad_i64_i32 v[74:75], s[10:11], v74, s29, v[142:143]
	v_cvt_pk_bf16_f32 v85, v76, v77
	s_cmp_eq_u32 s100, 1
	s_cbranch_scc1 .Lgi_st5
	global_store_dwordx4 v[100:101], v[82:85], off offset:256
.Lgi_st5:
	s_nop 1
	v_lshl_add_u64 v[82:83], v[74:75], 0, v[144:145]
	v_cvt_pk_bf16_f32 v74, v86, v87
	v_cvt_pk_bf16_f32 v75, v88, v89
	v_cvt_pk_bf16_f32 v76, v78, v79
	v_cvt_pk_bf16_f32 v77, v80, v81
	s_cmp_eq_u32 s100, 2
	s_cbranch_scc1 .Lgi_st6
	global_store_dwordx4 v[82:83], v[74:77], off
.Lgi_st6:
	v_cvt_pk_bf16_f32 v70, v70, v71
	v_cvt_pk_bf16_f32 v71, v72, v73
	v_cvt_pk_bf16_f32 v72, v66, v67
	v_add_u32_e32 v66, 0x80, v152
	v_mad_i64_i32 v[66:67], s[10:11], v66, s29, v[142:143]
	v_lshl_add_u64 v[66:67], v[66:67], 0, v[144:145]
	v_cvt_pk_bf16_f32 v73, v68, v69
	s_cmp_eq_u32 s100, 1
	s_cbranch_scc1 .Lgi_st7
	global_store_dwordx4 v[82:83], v[70:73], off offset:256
.Lgi_st7:
	v_cvt_pk_bf16_f32 v62, v62, v63
	v_cvt_pk_bf16_f32 v63, v64, v65
	v_cvt_pk_bf16_f32 v64, v58, v59
	v_cvt_pk_bf16_f32 v65, v60, v61
	s_cmp_eq_u32 s100, 2
	s_cbranch_scc1 .Lgi_st8
	global_store_dwordx4 v[66:67], v[62:65], off
.Lgi_st8:
	v_cvt_pk_bf16_f32 v50, v50, v51
	v_cvt_pk_bf16_f32 v51, v52, v53
	v_cvt_pk_bf16_f32 v52, v42, v43
	v_add_u32_e32 v42, 0x90, v152
	v_mad_i64_i32 v[42:43], s[10:11], v42, s29, v[142:143]
	v_cvt_pk_bf16_f32 v53, v44, v45
	s_cmp_eq_u32 s100, 1
	s_cbranch_scc1 .Lgi_st9
	global_store_dwordx4 v[66:67], v[50:53], off offset:256
.Lgi_st9:
	s_nop 1
	v_lshl_add_u64 v[50:51], v[42:43], 0, v[144:145]
	v_cvt_pk_bf16_f32 v42, v54, v55
	v_cvt_pk_bf16_f32 v43, v56, v57
	v_cvt_pk_bf16_f32 v44, v46, v47
	v_cvt_pk_bf16_f32 v45, v48, v49
	s_cmp_eq_u32 s100, 2
	s_cbranch_scc1 .Lgi_st10
	global_store_dwordx4 v[50:51], v[42:45], off
.Lgi_st10:
	v_cvt_pk_bf16_f32 v34, v34, v35
	v_cvt_pk_bf16_f32 v35, v36, v37
	v_cvt_pk_bf16_f32 v36, v26, v27
	v_add_u32_e32 v26, 0xa0, v152
	v_mad_i64_i32 v[26:27], s[10:11], v26, s29, v[142:143]
	v_cvt_pk_bf16_f32 v37, v28, v29
	s_cmp_eq_u32 s100, 1
	s_cbranch_scc1 .Lgi_st11
	global_store_dwordx4 v[50:51], v[34:37], off offset:256
.Lgi_st11:
	s_nop 1
	v_lshl_add_u64 v[34:35], v[26:27], 0, v[144:145]
	v_cvt_pk_bf16_f32 v26, v38, v39
	v_cvt_pk_bf16_f32 v27, v40, v41
	v_cvt_pk_bf16_f32 v28, v30, v31
	v_cvt_pk_bf16_f32 v29, v32, v33
	s_cmp_eq_u32 s100, 2
	s_cbranch_scc1 .Lgi_st12
	global_store_dwordx4 v[34:35], v[26:29], off
.Lgi_st12:
	v_cvt_pk_bf16_f32 v18, v18, v19
	v_cvt_pk_bf16_f32 v19, v20, v21
	v_cvt_pk_bf16_f32 v20, v10, v11
	v_add_u32_e32 v10, 0xb0, v152
	v_mad_i64_i32 v[10:11], s[10:11], v10, s29, v[142:143]
	v_cvt_pk_bf16_f32 v21, v12, v13
	s_cmp_eq_u32 s100, 1
	s_cbranch_scc1 .Lgi_st13
	global_store_dwordx4 v[34:35], v[18:21], off offset:256
.Lgi_st13:
	s_nop 1
	v_lshl_add_u64 v[18:19], v[10:11], 0, v[144:145]
	v_cvt_pk_bf16_f32 v10, v22, v23
	v_cvt_pk_bf16_f32 v11, v24, v25
	v_cvt_pk_bf16_f32 v12, v14, v15
	v_cvt_pk_bf16_f32 v13, v16, v17
	s_cmp_eq_u32 s100, 2
	s_cbranch_scc1 .Lgi_st14
	global_store_dwordx4 v[18:19], v[10:13], off
.Lgi_st14:
	v_cvt_pk_bf16_f32 v6, v6, v7
	v_cvt_pk_bf16_f32 v7, v8, v9
	v_cvt_pk_bf16_f32 v8, v2, v3
	v_cvt_pk_bf16_f32 v9, v4, v5
	s_cmp_eq_u32 s100, 1
	s_cbranch_scc1 .Lgi_st15
	global_store_dwordx4 v[18:19], v[6:9], off offset:256
.Lgi_st15:
	s_cbranch_vccnz .LBB0_297
	s_andn2_b64 vcc, exec, s[4:5]
	s_cbranch_vccnz .LBB0_296
	s_barrier
	s_branch .LBB0_296
.Lgi_h0_loop:
	s_add_u32 s10, s54, 0xfff80080
	s_addc_u32 s11, s55, -1
	s_add_i32 s12, 0, 0x10000
	s_cmp_eq_u32 s73, 28
	s_cselect_b32 s57, s45, s11
	s_cselect_b32 s56, s69, s10
	s_cselect_b32 s21, s43, s72
	s_cselect_b32 s20, s70, s71
	s_add_i32 s13, 0, 0x14000
	v_add_u32_e32 v158, s12, v147
	v_add_u32_e32 v174, s13, v147
	ds_read_b128 v[142:145], v158
	ds_read_b128 v[150:153], v158 offset:1024
	ds_read_b128 v[154:157], v158 offset:2048
	ds_read_b128 v[158:161], v158 offset:3072
	v_lshl_add_u64 v[194:195], s[54:55], 0, v[138:139]
	s_add_i32 m0, s59, 0xc000
	ds_read_b128 v[178:181], v149
	ds_read_b128 v[182:185], v149 offset:1024
	ds_read_b128 v[186:189], v149 offset:2048
	ds_read_b128 v[190:193], v149 offset:3072
	ds_read_b128 v[208:211], v149 offset:4096
	ds_read_b128 v[212:215], v149 offset:5120
	ds_read_b128 v[216:219], v149 offset:6144
	ds_read_b128 v[220:223], v149 offset:7168
	global_load_lds_dwordx4 v[194:195], off
	v_lshl_add_u64 v[194:195], s[54:55], 0, v[140:141]
	s_add_i32 m0, s59, 0xe000
	s_nop 0
	global_load_lds_dwordx4 v[194:195], off
	s_waitcnt vmcnt(8)
	s_waitcnt lgkmcnt(0)
	s_barrier
	s_setprio 1
	s_waitcnt lgkmcnt(0)
	v_mfma_f32_16x16x32_bf16 v[128:131], v[142:145], v[178:181], v[128:131]
	v_mfma_f32_16x16x32_bf16 v[124:127], v[154:157], v[178:181], v[124:127]
	v_mfma_f32_16x16x32_bf16 v[120:123], v[142:145], v[186:189], v[120:123]
	v_mfma_f32_16x16x32_bf16 v[112:115], v[154:157], v[186:189], v[112:115]
	v_mfma_f32_16x16x32_bf16 v[104:107], v[142:145], v[208:211], v[104:107]
	v_mfma_f32_16x16x32_bf16 v[94:97], v[154:157], v[208:211], v[94:97]
	v_mfma_f32_16x16x32_bf16 v[86:89], v[142:145], v[216:219], v[86:89]
	v_mfma_f32_16x16x32_bf16 v[78:81], v[154:157], v[216:219], v[78:81]
	v_mfma_f32_16x16x32_bf16 v[128:131], v[150:153], v[182:185], v[128:131]
	v_mfma_f32_16x16x32_bf16 v[124:127], v[158:161], v[182:185], v[124:127]
	v_mfma_f32_16x16x32_bf16 v[120:123], v[150:153], v[190:193], v[120:123]
	v_mfma_f32_16x16x32_bf16 v[112:115], v[158:161], v[190:193], v[112:115]
	v_mfma_f32_16x16x32_bf16 v[104:107], v[150:153], v[212:215], v[104:107]
	v_mfma_f32_16x16x32_bf16 v[94:97], v[158:161], v[212:215], v[94:97]
	v_mfma_f32_16x16x32_bf16 v[86:89], v[150:153], v[220:223], v[86:89]
	v_mfma_f32_16x16x32_bf16 v[78:81], v[158:161], v[220:223], v[78:81]
	s_setprio 0
	s_setprio 1
	s_setprio 0
	s_barrier
	s_add_i32 s10, s12, s58
	v_lshl_add_u64 v[194:195], s[20:21], 0, v[136:137]
	s_mov_b32 m0, s10
	ds_read_b128 v[178:181], v149 offset:16384
	ds_read_b128 v[182:185], v149 offset:17408
	ds_read_b128 v[186:189], v149 offset:18432
	ds_read_b128 v[190:193], v149 offset:19456
	ds_read_b128 v[208:211], v149 offset:20480
	ds_read_b128 v[212:215], v149 offset:21504
	ds_read_b128 v[216:219], v149 offset:22528
	ds_read_b128 v[220:223], v149 offset:23552
	global_load_lds_dwordx4 v[194:195], off
	s_add_i32 m0, s10, 0x2000
	s_add_u32 s10, s20, 0x4000
	v_lshl_add_u64 v[194:195], s[20:21], 0, v[132:133]
	s_addc_u32 s11, s21, 0
	s_add_i32 s12, s13, s58
	global_load_lds_dwordx4 v[194:195], off
	v_lshl_add_u64 v[194:195], s[10:11], 0, v[136:137]
	s_mov_b32 m0, s12
	v_lshl_add_u64 v[196:197], s[56:57], 0, v[134:135]
	global_load_lds_dwordx4 v[194:195], off
	v_lshl_add_u64 v[194:195], s[10:11], 0, v[132:133]
	s_add_i32 m0, s12, 0x2000
	s_nop 0
	global_load_lds_dwordx4 v[194:195], off
	v_lshl_add_u64 v[194:195], s[56:57], 0, v[98:99]
	s_mov_b32 m0, s59
	s_nop 0
	global_load_lds_dwordx4 v[194:195], off
	s_mov_b32 m0, s60
	s_nop 0
	global_load_lds_dwordx4 v[196:197], off
	s_waitcnt vmcnt(8)
	s_waitcnt lgkmcnt(0)
	s_barrier
	s_setprio 1
	s_waitcnt lgkmcnt(0)
	v_mfma_f32_16x16x32_bf16 v[62:65], v[142:145], v[178:181], v[62:65]
	v_mfma_f32_16x16x32_bf16 v[58:61], v[154:157], v[178:181], v[58:61]
	v_mfma_f32_16x16x32_bf16 v[54:57], v[142:145], v[186:189], v[54:57]
	v_mfma_f32_16x16x32_bf16 v[46:49], v[154:157], v[186:189], v[46:49]
	v_mfma_f32_16x16x32_bf16 v[38:41], v[142:145], v[208:211], v[38:41]
	v_mfma_f32_16x16x32_bf16 v[30:33], v[154:157], v[208:211], v[30:33]
	v_mfma_f32_16x16x32_bf16 v[22:25], v[142:145], v[216:219], v[22:25]
	v_mfma_f32_16x16x32_bf16 v[14:17], v[154:157], v[216:219], v[14:17]
	v_mfma_f32_16x16x32_bf16 v[62:65], v[150:153], v[182:185], v[62:65]
	v_mfma_f32_16x16x32_bf16 v[58:61], v[158:161], v[182:185], v[58:61]
	v_mfma_f32_16x16x32_bf16 v[54:57], v[150:153], v[190:193], v[54:57]
	v_mfma_f32_16x16x32_bf16 v[46:49], v[158:161], v[190:193], v[46:49]
	v_mfma_f32_16x16x32_bf16 v[38:41], v[150:153], v[212:215], v[38:41]
	v_mfma_f32_16x16x32_bf16 v[30:33], v[158:161], v[212:215], v[30:33]
	v_mfma_f32_16x16x32_bf16 v[22:25], v[150:153], v[220:223], v[22:25]
	v_mfma_f32_16x16x32_bf16 v[14:17], v[158:161], v[220:223], v[14:17]
	s_setprio 0
	s_setprio 1
	s_setprio 0
	s_barrier
	s_add_i32 s12, 0, 0x18000
	s_add_i32 s13, 0, 0x1c000
	v_add_u32_e32 v158, s12, v147
	v_add_u32_e32 v174, s13, v147
	ds_read_b128 v[142:145], v158
	ds_read_b128 v[150:153], v158 offset:1024
	ds_read_b128 v[154:157], v158 offset:2048
	ds_read_b128 v[158:161], v158 offset:3072
	s_add_u32 s10, s56, 0x80000
	s_addc_u32 s11, s57, 0
	s_mov_b32 m0, s61
	v_lshl_add_u64 v[198:199], s[10:11], 0, v[98:99]
	ds_read_b128 v[178:181], v149 offset:32768
	ds_read_b128 v[182:185], v149 offset:33792
	ds_read_b128 v[186:189], v149 offset:34816
	ds_read_b128 v[190:193], v149 offset:35840
	ds_read_b128 v[208:211], v149 offset:36864
	ds_read_b128 v[212:215], v149 offset:37888
	ds_read_b128 v[216:219], v149 offset:38912
	ds_read_b128 v[220:223], v149 offset:39936
	global_load_lds_dwordx4 v[198:199], off
	v_lshl_add_u64 v[198:199], s[10:11], 0, v[134:135]
	s_mov_b32 m0, s62
	s_nop 0
	global_load_lds_dwordx4 v[198:199], off
	s_waitcnt vmcnt(8)
	s_waitcnt lgkmcnt(0)
	s_barrier
	s_setprio 1
	s_waitcnt lgkmcnt(0)
	v_mfma_f32_16x16x32_bf16 v[128:131], v[142:145], v[178:181], v[128:131]
	v_mfma_f32_16x16x32_bf16 v[124:127], v[154:157], v[178:181], v[124:127]
	v_mfma_f32_16x16x32_bf16 v[120:123], v[142:145], v[186:189], v[120:123]
	v_mfma_f32_16x16x32_bf16 v[112:115], v[154:157], v[186:189], v[112:115]
	v_mfma_f32_16x16x32_bf16 v[104:107], v[142:145], v[208:211], v[104:107]
	v_mfma_f32_16x16x32_bf16 v[94:97], v[154:157], v[208:211], v[94:97]
	v_mfma_f32_16x16x32_bf16 v[86:89], v[142:145], v[216:219], v[86:89]
	v_mfma_f32_16x16x32_bf16 v[78:81], v[154:157], v[216:219], v[78:81]
	v_mfma_f32_16x16x32_bf16 v[128:131], v[150:153], v[182:185], v[128:131]
	v_mfma_f32_16x16x32_bf16 v[124:127], v[158:161], v[182:185], v[124:127]
	v_mfma_f32_16x16x32_bf16 v[120:123], v[150:153], v[190:193], v[120:123]
	v_mfma_f32_16x16x32_bf16 v[112:115], v[158:161], v[190:193], v[112:115]
	v_mfma_f32_16x16x32_bf16 v[104:107], v[150:153], v[212:215], v[104:107]
	v_mfma_f32_16x16x32_bf16 v[94:97], v[158:161], v[212:215], v[94:97]
	v_mfma_f32_16x16x32_bf16 v[86:89], v[150:153], v[220:223], v[86:89]
	v_mfma_f32_16x16x32_bf16 v[78:81], v[158:161], v[220:223], v[78:81]
	s_setprio 0
	s_setprio 1
	s_setprio 0
	s_barrier
	s_add_u32 s10, s20, 0x8000
	s_addc_u32 s11, s21, 0
	s_add_i32 s12, s12, s58
	v_lshl_add_u64 v[198:199], s[10:11], 0, v[136:137]
	s_mov_b32 m0, s12
	ds_read_b128 v[178:181], v149 offset:49152
	ds_read_b128 v[182:185], v149 offset:50176
	ds_read_b128 v[186:189], v149 offset:51200
	ds_read_b128 v[190:193], v149 offset:52224
	ds_read_b128 v[208:211], v149 offset:53248
	ds_read_b128 v[212:215], v149 offset:54272
	ds_read_b128 v[216:219], v149 offset:55296
	ds_read_b128 v[220:223], v149 offset:56320
	global_load_lds_dwordx4 v[198:199], off
	s_add_i32 m0, s12, 0x2000
	v_lshl_add_u64 v[198:199], s[10:11], 0, v[132:133]
	s_add_u32 s10, s20, 0xc000
	s_addc_u32 s11, s21, 0
	s_add_i32 s12, s13, s58
	global_load_lds_dwordx4 v[198:199], off
	v_lshl_add_u64 v[198:199], s[10:11], 0, v[136:137]
	s_mov_b32 m0, s12
	v_lshl_add_u64 v[194:195], v[194:195], 0, s[24:25]
	global_load_lds_dwordx4 v[198:199], off
	v_lshl_add_u64 v[198:199], s[10:11], 0, v[132:133]
	s_add_i32 m0, s12, 0x2000
	s_nop 0
	global_load_lds_dwordx4 v[198:199], off
	s_mov_b32 m0, s63
	s_nop 0
	global_load_lds_dwordx4 v[194:195], off
	v_lshl_add_u64 v[194:195], v[196:197], 0, s[24:25]
	s_mov_b32 m0, s64
	s_nop 0
	global_load_lds_dwordx4 v[194:195], off
	s_waitcnt vmcnt(8)
	s_waitcnt lgkmcnt(0)
	s_barrier
	s_setprio 1
	s_waitcnt lgkmcnt(0)
	v_mfma_f32_16x16x32_bf16 v[62:65], v[142:145], v[178:181], v[62:65]
	v_mfma_f32_16x16x32_bf16 v[58:61], v[154:157], v[178:181], v[58:61]
	v_mfma_f32_16x16x32_bf16 v[54:57], v[142:145], v[186:189], v[54:57]
	v_mfma_f32_16x16x32_bf16 v[46:49], v[154:157], v[186:189], v[46:49]
	v_mfma_f32_16x16x32_bf16 v[38:41], v[142:145], v[208:211], v[38:41]
	v_mfma_f32_16x16x32_bf16 v[30:33], v[154:157], v[208:211], v[30:33]
	v_mfma_f32_16x16x32_bf16 v[22:25], v[142:145], v[216:219], v[22:25]
	v_mfma_f32_16x16x32_bf16 v[14:17], v[154:157], v[216:219], v[14:17]
	v_mfma_f32_16x16x32_bf16 v[62:65], v[150:153], v[182:185], v[62:65]
	v_mfma_f32_16x16x32_bf16 v[58:61], v[158:161], v[182:185], v[58:61]
	v_mfma_f32_16x16x32_bf16 v[54:57], v[150:153], v[190:193], v[54:57]
	v_mfma_f32_16x16x32_bf16 v[46:49], v[158:161], v[190:193], v[46:49]
	v_mfma_f32_16x16x32_bf16 v[38:41], v[150:153], v[212:215], v[38:41]
	v_mfma_f32_16x16x32_bf16 v[30:33], v[158:161], v[212:215], v[30:33]
	v_mfma_f32_16x16x32_bf16 v[22:25], v[150:153], v[220:223], v[22:25]
	v_mfma_f32_16x16x32_bf16 v[14:17], v[158:161], v[220:223], v[14:17]
	s_setprio 0
	s_setprio 1
	s_setprio 0
	s_barrier
	s_add_i32 s73, s73, 2
	s_add_u32 s71, s71, 0x10000
	s_addc_u32 s72, s72, 0
	s_add_u32 s54, s54, 0x100
	s_addc_u32 s55, s55, 0
	s_cmp_gt_u32 s73, 29
	s_cbranch_scc0 .Lgi_h0_loop
	s_branch .Lgi_after_loop
.Lgi_h1_loop:
	s_add_u32 s10, s54, 0xfff80080
	s_addc_u32 s11, s55, -1
	s_add_i32 s12, 0, 0x10000
	s_cmp_eq_u32 s73, 28
	s_cselect_b32 s57, s45, s11
	s_cselect_b32 s56, s69, s10
	s_cselect_b32 s21, s43, s72
	s_cselect_b32 s20, s70, s71
	s_add_i32 s13, 0, 0x14000
	v_add_u32_e32 v158, s12, v147
	v_add_u32_e32 v174, s13, v147
	ds_read_b128 v[162:165], v174
	ds_read_b128 v[166:169], v174 offset:1024
	ds_read_b128 v[170:173], v174 offset:2048
	ds_read_b128 v[174:177], v174 offset:3072
	v_lshl_add_u64 v[194:195], s[54:55], 0, v[138:139]
	s_add_i32 m0, s59, 0xc000
	ds_read_b128 v[178:181], v149
	ds_read_b128 v[182:185], v149 offset:1024
	ds_read_b128 v[186:189], v149 offset:2048
	ds_read_b128 v[190:193], v149 offset:3072
	ds_read_b128 v[208:211], v149 offset:4096
	ds_read_b128 v[212:215], v149 offset:5120
	ds_read_b128 v[216:219], v149 offset:6144
	ds_read_b128 v[220:223], v149 offset:7168
	global_load_lds_dwordx4 v[194:195], off
	v_lshl_add_u64 v[194:195], s[54:55], 0, v[140:141]
	s_add_i32 m0, s59, 0xe000
	s_nop 0
	global_load_lds_dwordx4 v[194:195], off
	s_waitcnt vmcnt(8)
	s_waitcnt lgkmcnt(0)
	s_barrier
	s_setprio 1
	s_waitcnt lgkmcnt(0)
	s_setprio 0
	s_setprio 1
	v_mfma_f32_16x16x32_bf16 v[116:119], v[162:165], v[178:181], v[116:119]
	v_mfma_f32_16x16x32_bf16 v[108:111], v[170:173], v[178:181], v[108:111]
	v_mfma_f32_16x16x32_bf16 v[100:103], v[162:165], v[186:189], v[100:103]
	v_mfma_f32_16x16x32_bf16 v[90:93], v[170:173], v[186:189], v[90:93]
	v_mfma_f32_16x16x32_bf16 v[82:85], v[162:165], v[208:211], v[82:85]
	v_mfma_f32_16x16x32_bf16 v[74:77], v[170:173], v[208:211], v[74:77]
	v_mfma_f32_16x16x32_bf16 v[70:73], v[162:165], v[216:219], v[70:73]
	v_mfma_f32_16x16x32_bf16 v[66:69], v[170:173], v[216:219], v[66:69]
	v_mfma_f32_16x16x32_bf16 v[116:119], v[166:169], v[182:185], v[116:119]
	v_mfma_f32_16x16x32_bf16 v[108:111], v[174:177], v[182:185], v[108:111]
	v_mfma_f32_16x16x32_bf16 v[100:103], v[166:169], v[190:193], v[100:103]
	v_mfma_f32_16x16x32_bf16 v[90:93], v[174:177], v[190:193], v[90:93]
	v_mfma_f32_16x16x32_bf16 v[82:85], v[166:169], v[212:215], v[82:85]
	v_mfma_f32_16x16x32_bf16 v[74:77], v[174:177], v[212:215], v[74:77]
	v_mfma_f32_16x16x32_bf16 v[70:73], v[166:169], v[220:223], v[70:73]
	v_mfma_f32_16x16x32_bf16 v[66:69], v[174:177], v[220:223], v[66:69]
	s_setprio 0
	s_barrier
	s_add_i32 s10, s12, s58
	v_lshl_add_u64 v[194:195], s[20:21], 0, v[136:137]
	s_mov_b32 m0, s10
	ds_read_b128 v[178:181], v149 offset:16384
	ds_read_b128 v[182:185], v149 offset:17408
	ds_read_b128 v[186:189], v149 offset:18432
	ds_read_b128 v[190:193], v149 offset:19456
	ds_read_b128 v[208:211], v149 offset:20480
	ds_read_b128 v[212:215], v149 offset:21504
	ds_read_b128 v[216:219], v149 offset:22528
	ds_read_b128 v[220:223], v149 offset:23552
	global_load_lds_dwordx4 v[194:195], off
	s_add_i32 m0, s10, 0x2000
	s_add_u32 s10, s20, 0x4000
	v_lshl_add_u64 v[194:195], s[20:21], 0, v[132:133]
	s_addc_u32 s11, s21, 0
	s_add_i32 s12, s13, s58
	global_load_lds_dwordx4 v[194:195], off
	v_lshl_add_u64 v[194:195], s[10:11], 0, v[136:137]
	s_mov_b32 m0, s12
	v_lshl_add_u64 v[196:197], s[56:57], 0, v[134:135]
	global_load_lds_dwordx4 v[194:195], off
	v_lshl_add_u64 v[194:195], s[10:11], 0, v[132:133]
	s_add_i32 m0, s12, 0x2000
	s_nop 0
	global_load_lds_dwordx4 v[194:195], off
	v_lshl_add_u64 v[194:195], s[56:57], 0, v[98:99]
	s_mov_b32 m0, s59
	s_nop 0
	global_load_lds_dwordx4 v[194:195], off
	s_mov_b32 m0, s60
	s_nop 0
	global_load_lds_dwordx4 v[196:197], off
	s_waitcnt vmcnt(8)
	s_waitcnt lgkmcnt(0)
	s_barrier
	s_setprio 1
	s_waitcnt lgkmcnt(0)
	s_setprio 0
	s_setprio 1
	v_mfma_f32_16x16x32_bf16 v[50:53], v[162:165], v[178:181], v[50:53]
	v_mfma_f32_16x16x32_bf16 v[42:45], v[170:173], v[178:181], v[42:45]
	v_mfma_f32_16x16x32_bf16 v[34:37], v[162:165], v[186:189], v[34:37]
	v_mfma_f32_16x16x32_bf16 v[26:29], v[170:173], v[186:189], v[26:29]
	v_mfma_f32_16x16x32_bf16 v[18:21], v[162:165], v[208:211], v[18:21]
	v_mfma_f32_16x16x32_bf16 v[10:13], v[170:173], v[208:211], v[10:13]
	v_mfma_f32_16x16x32_bf16 v[6:9], v[162:165], v[216:219], v[6:9]
	v_mfma_f32_16x16x32_bf16 v[2:5], v[170:173], v[216:219], v[2:5]
	v_mfma_f32_16x16x32_bf16 v[50:53], v[166:169], v[182:185], v[50:53]
	v_mfma_f32_16x16x32_bf16 v[42:45], v[174:177], v[182:185], v[42:45]
	v_mfma_f32_16x16x32_bf16 v[34:37], v[166:169], v[190:193], v[34:37]
	v_mfma_f32_16x16x32_bf16 v[26:29], v[174:177], v[190:193], v[26:29]
	v_mfma_f32_16x16x32_bf16 v[18:21], v[166:169], v[212:215], v[18:21]
	v_mfma_f32_16x16x32_bf16 v[10:13], v[174:177], v[212:215], v[10:13]
	v_mfma_f32_16x16x32_bf16 v[6:9], v[166:169], v[220:223], v[6:9]
	v_mfma_f32_16x16x32_bf16 v[2:5], v[174:177], v[220:223], v[2:5]
	s_setprio 0
	s_barrier
	s_add_i32 s12, 0, 0x18000
	s_add_i32 s13, 0, 0x1c000
	v_add_u32_e32 v158, s12, v147
	v_add_u32_e32 v174, s13, v147
	ds_read_b128 v[162:165], v174
	ds_read_b128 v[166:169], v174 offset:1024
	ds_read_b128 v[170:173], v174 offset:2048
	ds_read_b128 v[174:177], v174 offset:3072
	s_add_u32 s10, s56, 0x80000
	s_addc_u32 s11, s57, 0
	s_mov_b32 m0, s61
	v_lshl_add_u64 v[198:199], s[10:11], 0, v[98:99]
	ds_read_b128 v[178:181], v149 offset:32768
	ds_read_b128 v[182:185], v149 offset:33792
	ds_read_b128 v[186:189], v149 offset:34816
	ds_read_b128 v[190:193], v149 offset:35840
	ds_read_b128 v[208:211], v149 offset:36864
	ds_read_b128 v[212:215], v149 offset:37888
	ds_read_b128 v[216:219], v149 offset:38912
	ds_read_b128 v[220:223], v149 offset:39936
	global_load_lds_dwordx4 v[198:199], off
	v_lshl_add_u64 v[198:199], s[10:11], 0, v[134:135]
	s_mov_b32 m0, s62
	s_nop 0
	global_load_lds_dwordx4 v[198:199], off
	s_waitcnt vmcnt(8)
	s_waitcnt lgkmcnt(0)
	s_barrier
	s_setprio 1
	s_waitcnt lgkmcnt(0)
	s_setprio 0
	s_setprio 1
	v_mfma_f32_16x16x32_bf16 v[116:119], v[162:165], v[178:181], v[116:119]
	v_mfma_f32_16x16x32_bf16 v[108:111], v[170:173], v[178:181], v[108:111]
	v_mfma_f32_16x16x32_bf16 v[100:103], v[162:165], v[186:189], v[100:103]
	v_mfma_f32_16x16x32_bf16 v[90:93], v[170:173], v[186:189], v[90:93]
	v_mfma_f32_16x16x32_bf16 v[82:85], v[162:165], v[208:211], v[82:85]
	v_mfma_f32_16x16x32_bf16 v[74:77], v[170:173], v[208:211], v[74:77]
	v_mfma_f32_16x16x32_bf16 v[70:73], v[162:165], v[216:219], v[70:73]
	v_mfma_f32_16x16x32_bf16 v[66:69], v[170:173], v[216:219], v[66:69]
	v_mfma_f32_16x16x32_bf16 v[116:119], v[166:169], v[182:185], v[116:119]
	v_mfma_f32_16x16x32_bf16 v[108:111], v[174:177], v[182:185], v[108:111]
	v_mfma_f32_16x16x32_bf16 v[100:103], v[166:169], v[190:193], v[100:103]
	v_mfma_f32_16x16x32_bf16 v[90:93], v[174:177], v[190:193], v[90:93]
	v_mfma_f32_16x16x32_bf16 v[82:85], v[166:169], v[212:215], v[82:85]
	v_mfma_f32_16x16x32_bf16 v[74:77], v[174:177], v[212:215], v[74:77]
	v_mfma_f32_16x16x32_bf16 v[70:73], v[166:169], v[220:223], v[70:73]
	v_mfma_f32_16x16x32_bf16 v[66:69], v[174:177], v[220:223], v[66:69]
	s_setprio 0
	s_barrier
	s_add_u32 s10, s20, 0x8000
	s_addc_u32 s11, s21, 0
	s_add_i32 s12, s12, s58
	v_lshl_add_u64 v[198:199], s[10:11], 0, v[136:137]
	s_mov_b32 m0, s12
	ds_read_b128 v[178:181], v149 offset:49152
	ds_read_b128 v[182:185], v149 offset:50176
	ds_read_b128 v[186:189], v149 offset:51200
	ds_read_b128 v[190:193], v149 offset:52224
	ds_read_b128 v[208:211], v149 offset:53248
	ds_read_b128 v[212:215], v149 offset:54272
	ds_read_b128 v[216:219], v149 offset:55296
	ds_read_b128 v[220:223], v149 offset:56320
	global_load_lds_dwordx4 v[198:199], off
	s_add_i32 m0, s12, 0x2000
	v_lshl_add_u64 v[198:199], s[10:11], 0, v[132:133]
	s_add_u32 s10, s20, 0xc000
	s_addc_u32 s11, s21, 0
	s_add_i32 s12, s13, s58
	global_load_lds_dwordx4 v[198:199], off
	v_lshl_add_u64 v[198:199], s[10:11], 0, v[136:137]
	s_mov_b32 m0, s12
	v_lshl_add_u64 v[194:195], v[194:195], 0, s[24:25]
	global_load_lds_dwordx4 v[198:199], off
	v_lshl_add_u64 v[198:199], s[10:11], 0, v[132:133]
	s_add_i32 m0, s12, 0x2000
	s_nop 0
	global_load_lds_dwordx4 v[198:199], off
	s_mov_b32 m0, s63
	s_nop 0
	global_load_lds_dwordx4 v[194:195], off
	v_lshl_add_u64 v[194:195], v[196:197], 0, s[24:25]
	s_mov_b32 m0, s64
	s_nop 0
	global_load_lds_dwordx4 v[194:195], off
	s_waitcnt vmcnt(8)
	s_waitcnt lgkmcnt(0)
	s_barrier
	s_setprio 1
	s_waitcnt lgkmcnt(0)
	s_setprio 0
	s_setprio 1
	v_mfma_f32_16x16x32_bf16 v[50:53], v[162:165], v[178:181], v[50:53]
	v_mfma_f32_16x16x32_bf16 v[42:45], v[170:173], v[178:181], v[42:45]
	v_mfma_f32_16x16x32_bf16 v[34:37], v[162:165], v[186:189], v[34:37]
	v_mfma_f32_16x16x32_bf16 v[26:29], v[170:173], v[186:189], v[26:29]
	v_mfma_f32_16x16x32_bf16 v[18:21], v[162:165], v[208:211], v[18:21]
	v_mfma_f32_16x16x32_bf16 v[10:13], v[170:173], v[208:211], v[10:13]
	v_mfma_f32_16x16x32_bf16 v[6:9], v[162:165], v[216:219], v[6:9]
	v_mfma_f32_16x16x32_bf16 v[2:5], v[170:173], v[216:219], v[2:5]
	v_mfma_f32_16x16x32_bf16 v[50:53], v[166:169], v[182:185], v[50:53]
	v_mfma_f32_16x16x32_bf16 v[42:45], v[174:177], v[182:185], v[42:45]
	v_mfma_f32_16x16x32_bf16 v[34:37], v[166:169], v[190:193], v[34:37]
	v_mfma_f32_16x16x32_bf16 v[26:29], v[174:177], v[190:193], v[26:29]
	v_mfma_f32_16x16x32_bf16 v[18:21], v[166:169], v[212:215], v[18:21]
	v_mfma_f32_16x16x32_bf16 v[10:13], v[174:177], v[212:215], v[10:13]
	v_mfma_f32_16x16x32_bf16 v[6:9], v[166:169], v[220:223], v[6:9]
	v_mfma_f32_16x16x32_bf16 v[2:5], v[174:177], v[220:223], v[2:5]
	s_setprio 0
	s_barrier
	s_add_i32 s73, s73, 2
	s_add_u32 s71, s71, 0x10000
	s_addc_u32 s72, s72, 0
	s_add_u32 s54, s54, 0x100
	s_addc_u32 s55, s55, 0
	s_cmp_gt_u32 s73, 29
	s_cbranch_scc0 .Lgi_h1_loop
	s_branch .Lgi_after_loop
